# strategy 1 (wait consolidation): MLA tile-end block waits once (vmcnt(0)) before the five staging ds_writes instead of a 5-step counted ladder
# speedup vs baseline: 1.0031x; 1.0031x over previous
; #define MFMA(a, b, c) __builtin_amdgcn_mfma_f32_32x32x16_bf16((a), (b), (c), 0, 0, 0)
; DI unsigned pack2(float a, float b) { f32x2 v = {a, b}; return __builtin_bit_cast(unsigned, __builtin_convertvector(v, bf16v2)); }
; template <int DK, int MODE> ...
;     ...
;           s0[e] = __builtin_amdgcn_exp2f(s0[e] - m); s0[e + 1] = __builtin_amdgcn_exp2f(s0[e + 1] - m); s0[e + 2] = __builtin_amdgcn_exp2f(s0[e + 2] - m); s0[e + 3] = __builtin_amdgcn_exp2f(s0[e + 3] - m);
;           ps0 += s0[e]; ps1 += s0[e + 1]; ps2 += s0[e + 2]; ps3 += s0[e + 3];
;         }
; #pragma unroll
;         for (int e = 0; e < 16; e += 4) {
;           s1[e] = __builtin_amdgcn_exp2f(s1[e] - m); s1[e + 1] = __builtin_amdgcn_exp2f(s1[e + 1] - m); s1[e + 2] = __builtin_amdgcn_exp2f(s1[e + 2] - m); s1[e + 3] = __builtin_amdgcn_exp2f(s1[e + 3] - m);
;           ps0 += s1[e]; ps1 += s1[e + 1]; ps2 += s1[e + 2]; ps3 += s1[e + 3];
;         }
;         lsum += (ps0 + ps1) + (ps2 + ps3);
;     ...
; #pragma unroll
;       for (int j = 0; j < 2; ++j) {
;         u32x4 a, b;
;         a.x = pack2(s0[8 * j], s0[8 * j + 1]); a.y = pack2(s0[8 * j + 2], s0[8 * j + 3]); a.z = pack2(s0[8 * j + 4], s0[8 * j + 5]); a.w = pack2(s0[8 * j + 6], s0[8 * j + 7]);
;         b.x = pack2(s1[8 * j], s1[8 * j + 1]); b.y = pack2(s1[8 * j + 2], s1[8 * j + 3]); b.z = pack2(s1[8 * j + 4], s1[8 * j + 5]); b.w = pack2(s1[8 * j + 6], s1[8 * j + 7]);
;         pf[j] = __builtin_bit_cast(bf16x8, a); pf[2 + j] = __builtin_bit_cast(bf16x8, b);
;       }
;       __builtin_amdgcn_s_setprio(1);
; #pragma unroll
;       for (int j = 0; j < 4; ++j) { o0 = MFMA(vf0[j], pf[j], o0); o1 = MFMA(vf1[j], pf[j], o1); }
;       __builtin_amdgcn_s_setprio(0);
;     }
;     __builtin_amdgcn_sched_barrier(0);
;     if (more) swrite(cur ^ 1);
.LBB0_524:
	v_sub_f32_e32 v0, v64, v155
	v_exp_f32_e32 v14, v0
	v_sub_f32_e32 v0, v65, v155
	v_exp_f32_e32 v64, v0
	v_sub_f32_e32 v0, v66, v155
	v_exp_f32_e32 v15, v0
	v_sub_f32_e32 v0, v67, v155
	v_exp_f32_e32 v65, v0
	v_sub_f32_e32 v0, v68, v155
	v_exp_f32_e32 v66, v0
	v_sub_f32_e32 v0, v69, v155
	v_exp_f32_e32 v68, v0
	v_sub_f32_e32 v0, v70, v155
	v_exp_f32_e32 v67, v0
	v_sub_f32_e32 v0, v71, v155
	v_exp_f32_e32 v69, v0
	v_sub_f32_e32 v0, v72, v155
	v_exp_f32_e32 v70, v0
	v_sub_f32_e32 v0, v73, v155
	v_exp_f32_e32 v72, v0
	v_sub_f32_e32 v0, v74, v155
	v_exp_f32_e32 v71, v0
	v_sub_f32_e32 v0, v75, v155
	v_exp_f32_e32 v73, v0
	v_sub_f32_e32 v0, v76, v155
	v_exp_f32_e32 v74, v0
	v_sub_f32_e32 v0, v77, v155
	v_exp_f32_e32 v76, v0
	v_sub_f32_e32 v0, v78, v155
	v_exp_f32_e32 v75, v0
	v_sub_f32_e32 v0, v79, v155
	v_exp_f32_e32 v77, v0
	v_sub_f32_e32 v0, v48, v155
	v_exp_f32_e32 v78, v0
	v_sub_f32_e32 v0, v49, v155
	v_exp_f32_e32 v176, v0
	v_sub_f32_e32 v0, v50, v155
	v_exp_f32_e32 v79, v0
	v_sub_f32_e32 v0, v51, v155
	v_exp_f32_e32 v177, v0
	v_sub_f32_e32 v0, v52, v155
	v_exp_f32_e32 v178, v0
	v_sub_f32_e32 v0, v53, v155
	v_exp_f32_e32 v180, v0
	v_sub_f32_e32 v0, v54, v155
	v_exp_f32_e32 v179, v0
	v_sub_f32_e32 v0, v55, v155
	v_exp_f32_e32 v181, v0
	v_sub_f32_e32 v0, v56, v155
	v_exp_f32_e32 v182, v0
	v_sub_f32_e32 v0, v57, v155
	v_exp_f32_e32 v184, v0
	v_sub_f32_e32 v0, v58, v155
	v_exp_f32_e32 v183, v0
	v_sub_f32_e32 v0, v59, v155
	v_exp_f32_e32 v185, v0
	v_sub_f32_e32 v0, v60, v155
	v_exp_f32_e32 v186, v0
	v_sub_f32_e32 v0, v61, v155
	v_exp_f32_e32 v200, v0
	v_sub_f32_e32 v0, v62, v155
	v_pk_add_f32 v[48:49], v[66:67], v[14:15]
	v_pk_add_f32 v[50:51], v[68:69], v[64:65]
	v_exp_f32_e32 v187, v0
	v_sub_f32_e32 v0, v63, v155
	v_pk_add_f32 v[48:49], v[70:71], v[48:49]
	v_pk_add_f32 v[50:51], v[72:73], v[50:51]
	v_exp_f32_e32 v201, v0
	v_pk_add_f32 v[202:203], v[74:75], v[48:49]
	v_pk_add_f32 v[204:205], v[76:77], v[50:51]
	v_cvt_pk_bf16_f32 v48, v14, v64
	v_cvt_pk_bf16_f32 v49, v15, v65
	v_pk_add_f32 v[14:15], v[78:79], v[202:203]
	v_pk_add_f32 v[64:65], v[176:177], v[204:205]
	v_pk_add_f32 v[14:15], v[178:179], v[14:15]
	v_pk_add_f32 v[64:65], v[180:181], v[64:65]
	v_pk_add_f32 v[14:15], v[182:183], v[14:15]
	v_pk_add_f32 v[64:65], v[184:185], v[64:65]
	v_pk_add_f32 v[14:15], v[186:187], v[14:15]
	v_pk_add_f32 v[64:65], v[200:201], v[64:65]
	v_cvt_pk_bf16_f32 v50, v66, v68
	v_pk_add_f32 v[14:15], v[14:15], v[64:65]
	v_cvt_pk_bf16_f32 v51, v67, v69
	v_cvt_pk_bf16_f32 v52, v78, v176
	v_cvt_pk_bf16_f32 v53, v79, v177
	v_cvt_pk_bf16_f32 v54, v178, v180
	v_cvt_pk_bf16_f32 v55, v179, v181
	v_cvt_pk_bf16_f32 v56, v70, v72
	v_cvt_pk_bf16_f32 v57, v71, v73
	v_cvt_pk_bf16_f32 v58, v74, v76
	v_cvt_pk_bf16_f32 v59, v75, v77
	v_cvt_pk_bf16_f32 v60, v182, v184
	v_cvt_pk_bf16_f32 v61, v183, v185
	v_cvt_pk_bf16_f32 v62, v186, v200
	v_cvt_pk_bf16_f32 v63, v187, v201
	v_add_f32_e32 v0, v14, v15
	s_setprio 1
	v_mfma_f32_32x32x16_bf16 v[16:31], v[136:139], v[48:51], v[16:31]
	v_add_f32_e32 v151, v151, v0
	v_mfma_f32_32x32x16_bf16 v[32:47], v[140:143], v[48:51], v[32:47]
	v_mfma_f32_32x32x16_bf16 v[16:31], v[108:111], v[56:59], v[16:31]
	v_mfma_f32_32x32x16_bf16 v[32:47], v[132:135], v[56:59], v[32:47]
	v_mfma_f32_32x32x16_bf16 v[16:31], v[100:103], v[52:55], v[16:31]
	v_mfma_f32_32x32x16_bf16 v[32:47], v[104:107], v[52:55], v[32:47]
	v_mfma_f32_32x32x16_bf16 v[16:31], v[96:99], v[60:63], v[16:31]
	v_mfma_f32_32x32x16_bf16 v[32:47], v[92:95], v[60:63], v[32:47]
	s_setprio 0
	s_waitcnt vmcnt(0)
	ds_write_b128 v241, v[88:91]
	ds_write_b128 v242, v[84:87]
	ds_write_b128 v243, v[10:13]
	ds_write_b128 v244, v[6:9] offset:26624
	s_add_i32 s9, s9, 64
	s_add_i32 s10, s10, 1
	s_cmp_eq_u32 s2, s9
	ds_write_b128 v245, v[2:5] offset:26624
	s_branch .Lmla_sync
